# P2a q/k tile epilogue: the 10 rope-table load pairs (each followed by vmcnt(1)/vmcnt(0), which also waited for the previous group's stores) replaced by a rolling 3-deep prefetch into free registers wi
# baseline (speedup 1.0000x reference)
;     __device__ __forceinline__ void operator()(const f32x4 (&acc)[2][2][4][2], const pg8::Unit& u, int wr, int wc, int fr, int fq) const {
;     ...
;         if (kind == 0 || kind == 4) {
;             const bool isq = (kind == 0) && (u.pn < 4);
;             const float* gsrc = isq ? KIN(I_QG) : KIN(I_KG);
;             const float osc = isq ? QSCALE : 1.0f;
;             const f32x2* tab = (const f32x2*)(ws + WS_TAB);
;             f32x4 g[2][2];
; #pragma unroll
;             for (int bj = 0; bj < 2; ++bj)
; #pragma unroll
;                 for (int n = 0; n < 2; ++n) g[bj][n] = *(const f32x4*)(gsrc + 32 * bj + 16 * n + 4 * fq);
;             bf16_t* dst = (bf16_t*)(ws + (isq ? WS_Q : WS_K));
;             const int rowoff = (kind == 0 && !isq) ? CTXL : 0;
;             const int G = 4 * (u.pn & 3) + wc;
; #pragma unroll
;             for (int ai = 0; ai < 2; ++ai) {
;                 const int rpos = 4 * u.pm + 2 * ai + wr;
;                 f32x4 cr0, cr1;
;                 if (kind == 0) { const f32x4* tp = (const f32x4*)(tab + rpos * 16 + 4 * fq); cr0 = tp[0]; cr1 = tp[1]; }
;                 else { cr0 = (f32x4){1.f, 0.f, 1.f, 0.f}; cr1 = cr0; }
; #pragma unroll
;                 for (int m = 0; m < 4; ++m) {
;                     const int t = 256 * u.pm + 128 * ai + 64 * wr + 16 * m + fr;
;                     float ss = 0.f;
; #pragma unroll
;                     for (int bj = 0; bj < 2; ++bj)
; #pragma unroll
;                         for (int n = 0; n < 2; ++n) { const f32x4 v = acc[ai][bj][m][n]; ss += (v[0] * v[0] + v[1] * v[1]) + (v[2] * v[2] + v[3] * v[3]); }
;                     ss += __shfl_xor(ss, 16); ss += __shfl_xor(ss, 32);
;                     const float rstd = __builtin_amdgcn_rsqf(ss * (1.0f / 64.0f) + EPS) * osc;
;                     f32x4 cc0, cc1;
;                     if (kind == 0) { const f32x4* tp = (const f32x4*)(tab + (16 * m + fr) * 16 + 4 * fq); cc0 = tp[0]; cc1 = tp[1]; }
;                     else { cc0 = (f32x4){1.f, 0.f, 1.f, 0.f}; cc1 = cc0; }
.LBB0_359:
	v_lshlrev_b32_e32 v128, 2, v170
	global_load_dwordx4 v[152:155], v128, s[4:5]
	global_load_dwordx4 v[132:135], v128, s[4:5] offset:64
	global_load_dwordx4 v[148:151], v128, s[4:5] offset:128
	s_nop 0
	global_load_dwordx4 v[128:131], v128, s[4:5] offset:192
	v_lshlrev_b32_e32 v168, 3, v170
	v_lshl_add_u64 v[136:137], s[40:41], 0, v[168:169]
	v_lshl_add_u64 v[180:181], v[136:137], 0, s[16:17]
	v_mov_b32_e32 v230, s64
	v_lshl_add_u32 v230, v230, 6, s50
	v_ashrrev_i32_e32 v231, 31, v230
	v_lshl_add_u64 v[230:231], v[230:231], 3, v[180:181]
	global_load_dwordx4 v[216:219], v[230:231], off offset:16
	global_load_dwordx4 v[230:233], v[230:231], off
	v_lshlrev_b32_e32 v238, 3, v172
	v_mov_b32_e32 v239, 0
	v_lshl_add_u64 v[238:239], v[180:181], 0, v[238:239]
	global_load_dwordx4 v[234:237], v[238:239], off offset:16
	global_load_dwordx4 v[238:241], v[238:239], off
	v_lshlrev_b32_e32 v248, 3, v172
	v_mov_b32_e32 v249, 0
	v_lshl_add_u64 v[248:249], v[180:181], 0, v[248:249]
	global_load_dwordx4 v[242:245], v[248:249], off offset:2064
	global_load_dwordx4 v[248:251], v[248:249], off offset:2048
	v_cndmask_b32_e64 v136, 0, 1, s[20:21]
	v_mov_b32_e32 v188, 0
	v_mov_b32_e32 v144, 1.0
	v_cmp_ne_u32_e64 s[4:5], 1, v136
	s_andn2_b64 vcc, exec, s[20:21]
	v_mov_b32_e32 v136, 1.0
	v_mov_b32_e32 v182, 0
	v_mov_b32_e32 v183, 1.0
	v_mov_b32_e32 v137, 0
	v_mov_b32_e32 v140, 1.0
	v_mov_b32_e32 v184, 0
	v_mov_b32_e32 v185, 1.0
	v_mov_b32_e32 v141, 0
	s_cbranch_vccnz .LBB0_361
	s_waitcnt vmcnt(4)
	s_lshl_b32 s66, s64, 6
	s_add_i32 s66, s66, s50
	s_ashr_i32 s67, s66, 31
	v_lshl_add_u64 v[140:141], s[66:67], 3, v[180:181]
	v_mov_b32_e32 v136, v216
	v_mov_b32_e32 v137, v217
	v_mov_b32_e32 v138, v218
	v_mov_b32_e32 v139, v219
	s_nop 0
	v_mov_b32_e32 v140, v230
	v_mov_b32_e32 v141, v231
	v_mov_b32_e32 v142, v232
	v_mov_b32_e32 v143, v233
	v_mov_b32_e32 v182, v137
	v_mov_b32_e32 v183, v138
	v_mov_b32_e32 v137, v139
	v_mov_b32_e32 v184, v141
	v_mov_b32_e32 v185, v142
	v_mov_b32_e32 v141, v143
	v_lshlrev_b32_e32 v230, 3, v172
	v_mov_b32_e32 v231, 0
	v_lshl_add_u64 v[230:231], v[180:181], 0, v[230:231]
	v_lshl_add_u64 v[230:231], v[230:231], 0, s[18:19]
	global_load_dwordx4 v[216:219], v[230:231], off offset:16
	global_load_dwordx4 v[230:233], v[230:231], off
.LBB0_361:
	v_and_b32_e32 v139, 64, v203
	v_xor_b32_e32 v138, 16, v203
	v_add_u32_e32 v139, 64, v139
	v_cmp_lt_i32_e32 vcc, v138, v139
	v_mul_f32_e32 v142, v127, v127
	v_fmac_f32_e32 v142, v126, v126
	v_cndmask_b32_e32 v138, v203, v138, vcc
	v_lshlrev_b32_e32 v179, 2, v138
	v_mul_f32_e32 v138, v125, v125
	v_fmac_f32_e32 v138, v124, v124
	v_add_f32_e32 v138, v138, v142
	v_mul_f32_e32 v142, v121, v121
	v_mul_f32_e32 v143, v123, v123
	v_fmac_f32_e32 v142, v120, v120
	v_fmac_f32_e32 v143, v122, v122
	v_add_f32_e32 v142, v142, v143
	v_add_f32_e32 v138, v138, v142
	v_mul_f32_e32 v142, v117, v117
	v_mul_f32_e32 v143, v119, v119
	v_fmac_f32_e32 v142, v116, v116
	v_fmac_f32_e32 v143, v118, v118
	v_add_f32_e32 v142, v142, v143
	v_add_f32_e32 v138, v138, v142
	v_mul_f32_e32 v142, v113, v113
	v_mul_f32_e32 v143, v115, v115
	v_fmac_f32_e32 v142, v112, v112
	v_fmac_f32_e32 v143, v114, v114
	v_add_f32_e32 v142, v142, v143
	v_add_f32_e32 v138, v138, v142
	ds_bpermute_b32 v142, v179, v138
	v_xor_b32_e32 v143, 32, v203
	v_cmp_lt_i32_e32 vcc, v143, v139
	v_mov_b32_e32 v189, 1.0
	v_mov_b32_e32 v145, 0
	v_cndmask_b32_e32 v139, v203, v143, vcc
	v_lshlrev_b32_e32 v204, 2, v139
	s_waitcnt lgkmcnt(0)
	v_add_f32_e32 v138, v138, v142
	ds_bpermute_b32 v139, v204, v138
	s_and_b64 vcc, exec, s[4:5]
	v_mov_b32_e32 v156, 1.0
	v_mov_b32_e32 v190, 0
	v_mov_b32_e32 v191, 1.0
	v_mov_b32_e32 v157, 0
	s_cbranch_vccnz .LBB0_363
	s_waitcnt vmcnt(4)
	v_lshlrev_b32_e32 v168, 3, v172
	v_lshl_add_u64 v[142:143], v[180:181], 0, v[168:169]
	v_mov_b32_e32 v144, v234
	v_mov_b32_e32 v145, v235
	v_mov_b32_e32 v146, v236
	v_mov_b32_e32 v147, v237
	v_mov_b32_e32 v156, v238
	v_mov_b32_e32 v157, v239
	v_mov_b32_e32 v158, v240
	v_mov_b32_e32 v159, v241
	v_mov_b32_e32 v188, v145
	v_mov_b32_e32 v189, v146
	v_mov_b32_e32 v145, v147
	v_mov_b32_e32 v190, v157
	v_mov_b32_e32 v191, v158
	v_mov_b32_e32 v157, v159
	v_lshlrev_b32_e32 v238, 3, v172
	v_mov_b32_e32 v239, 0
	v_lshl_add_u64 v[238:239], v[180:181], 0, v[238:239]
	v_lshl_add_u64 v[238:239], v[238:239], 0, s[18:19]
	global_load_dwordx4 v[234:237], v[238:239], off offset:2064
	global_load_dwordx4 v[238:241], v[238:239], off offset:2048
; __device__ __forceinline__ unsigned cvtpk(float lo, float hi) { f32x2 v = {lo, hi}; bf16x2_t b = __builtin_convertvector(v, bf16x2_t); return __builtin_bit_cast(unsigned, b); }
;     __device__ __forceinline__ void operator()(const f32x4 (&acc)[2][2][4][2], const pg8::Unit& u, int wr, int wc, int fr, int fq) const {
;     ...
; #pragma unroll
;                 for (int m = 0; m < 4; ++m) {
;                     const int t = 256 * u.pm + 128 * ai + 64 * wr + 16 * m + fr;
;                     float ss = 0.f;
; #pragma unroll
;                     for (int bj = 0; bj < 2; ++bj)
; #pragma unroll
;                         for (int n = 0; n < 2; ++n) { const f32x4 v = acc[ai][bj][m][n]; ss += (v[0] * v[0] + v[1] * v[1]) + (v[2] * v[2] + v[3] * v[3]); }
;                     ss += __shfl_xor(ss, 16); ss += __shfl_xor(ss, 32);
;                     const float rstd = __builtin_amdgcn_rsqf(ss * (1.0f / 64.0f) + EPS) * osc;
;                     f32x4 cc0, cc1;
;                     if (kind == 0) { const f32x4* tp = (const f32x4*)(tab + (16 * m + fr) * 16 + 4 * fq); cc0 = tp[0]; cc1 = tp[1]; }
;                     else { cc0 = (f32x4){1.f, 0.f, 1.f, 0.f}; cc1 = cc0; }
;                     bf16_t* rowp = dst + (size_t)(rowoff + t) * 1024 + G * 64 + 8 * fq;
; #pragma unroll
;                     for (int bj = 0; bj < 2; ++bj) {
;                         const f32x4 x1 = acc[ai][bj][m][0] * g[bj][0] * rstd, x2 = acc[ai][bj][m][1] * g[bj][1] * rstd;
;                         const f32x4 ca = bj == 0 ? cr0 : cc0, cb = bj == 0 ? cr1 : cc1;
;                         const float co[4] = {ca[0], ca[2], cb[0], cb[2]}, si[4] = {ca[1], ca[3], cb[1], cb[3]};
;                         float o1[4], o2[4];
; #pragma unroll
;                         for (int e = 0; e < 4; ++e) { o1[e] = x1[e] * co[e] - x2[e] * si[e]; o2[e] = x2[e] * co[e] + x1[e] * si[e]; }
;                         u32x4 w; w.x = cvtpk(o1[0], o1[1]); w.y = cvtpk(o1[2], o1[3]); w.z = cvtpk(o2[0], o2[1]); w.w = cvtpk(o2[2], o2[3]);
;                         *(u32x4*)(rowp + 32 * bj) = w;
.LBB0_363:
	s_lshl_b32 s66, s64, 8
	s_add_u32 s40, s40, s42
	s_addc_u32 s41, s41, s43
	s_xor_b64 s[20:21], s[20:21], s[28:29]
	s_and_b64 s[20:21], s[20:21], exec
	s_waitcnt lgkmcnt(0)
	v_add_f32_e32 v138, v138, v139
	s_cselect_b32 s20, 0x100, 0
	s_lshl_b32 s21, s65, 2
	v_fmamk_f32 v138, v138, 0x3c800000, v202
	s_and_b32 s21, s21, 12
	v_rsq_f32_e32 v138, v138
	s_or_b32 s21, s21, s46
	v_add_u32_e32 v205, s20, v167
	s_lshl_b32 s20, s21, 7
	s_add_u32 s20, s40, s20
	v_add_u32_e32 v146, s66, v205
	s_addc_u32 s21, s41, 0
	v_lshlrev_b32_e32 v168, 1, v164
	v_ashrrev_i32_e32 v147, 31, v146
	v_mul_f32_e32 v206, s6, v138
	v_lshl_add_u64 v[138:139], s[20:21], 0, v[168:169]
	v_lshlrev_b64 v[142:143], 11, v[146:147]
	v_lshl_add_u64 v[208:209], v[138:139], 0, v[142:143]
	v_mov_b32_e32 v159, v121
	s_waitcnt vmcnt(10)
	v_mov_b32_e32 v143, v133
	v_mov_b32_e32 v121, v125
	v_mov_b32_e32 v133, v153
	v_mov_b32_e32 v158, v124
	v_mov_b32_e32 v142, v152
	v_pk_mul_f32 v[120:121], v[120:121], v[132:133]
	v_pk_mul_f32 v[158:159], v[158:159], v[142:143]
	v_pk_mul_f32 v[120:121], v[120:121], v[206:207] op_sel_hi:[1,0]
	v_pk_mul_f32 v[186:187], v[158:159], v[206:207] op_sel_hi:[1,0]
	v_pk_mul_f32 v[124:125], v[140:141], v[120:121]
	v_mov_b32_e32 v158, v184
	v_pk_fma_f32 v[210:211], v[184:185], v[186:187], v[124:125]
	v_mov_b32_e32 v125, v121
	v_mov_b32_e32 v159, v141
	v_mov_b32_e32 v121, v187
	v_mov_b32_e32 v152, v140
	v_mov_b32_e32 v153, v185
	v_mov_b32_e32 v124, v186
	v_pk_mul_f32 v[120:121], v[158:159], v[120:121]
	v_mov_b32_e32 v186, v126
	v_pk_fma_f32 v[120:121], v[152:153], v[124:125], v[120:121] neg_lo:[0,0,1] neg_hi:[0,0,1]
	v_mov_b32_e32 v187, v123
	v_mov_b32_e32 v124, v154
	v_mov_b32_e32 v125, v135
	v_mov_b32_e32 v123, v127
	v_mov_b32_e32 v135, v155
	v_pk_mul_f32 v[186:187], v[186:187], v[124:125]
	v_pk_mul_f32 v[122:123], v[122:123], v[134:135]
	v_pk_mul_f32 v[212:213], v[186:187], v[206:207] op_sel_hi:[1,0]
	v_pk_mul_f32 v[122:123], v[122:123], v[206:207] op_sel_hi:[1,0]
	v_mov_b32_e32 v186, v182
	v_pk_mul_f32 v[126:127], v[136:137], v[122:123]
	v_mov_b32_e32 v215, v123
	v_mov_b32_e32 v187, v137
	v_mov_b32_e32 v123, v213
	v_mov_b32_e32 v154, v136
	v_mov_b32_e32 v155, v183
	v_mov_b32_e32 v214, v212
	v_pk_mul_f32 v[122:123], v[186:187], v[122:123]
	v_pk_fma_f32 v[126:127], v[182:183], v[212:213], v[126:127]
	v_pk_fma_f32 v[122:123], v[154:155], v[214:215], v[122:123] neg_lo:[0,0,1] neg_hi:[0,0,1]
	v_cvt_pk_bf16_f32 v120, v120, v121
	v_cvt_pk_bf16_f32 v121, v122, v123
	v_cvt_pk_bf16_f32 v122, v210, v211
	v_cvt_pk_bf16_f32 v123, v126, v127
	global_store_dwordx4 v[208:209], v[120:123], off
	s_and_b64 vcc, exec, s[4:5]
	s_nop 0
	v_mov_b32_e32 v121, v113
	v_mov_b32_e32 v123, v129
	v_mov_b32_e32 v113, v117
	v_mov_b32_e32 v129, v149
	v_mov_b32_e32 v120, v116
	v_mov_b32_e32 v122, v148
	v_pk_mul_f32 v[112:113], v[112:113], v[128:129]
	v_pk_mul_f32 v[120:121], v[120:121], v[122:123]
	v_pk_mul_f32 v[112:113], v[112:113], v[206:207] op_sel_hi:[1,0]
	v_pk_mul_f32 v[120:121], v[120:121], v[206:207] op_sel_hi:[1,0]
	v_pk_mul_f32 v[116:117], v[112:113], v[156:157]
	v_mov_b32_e32 v127, v113
	v_pk_fma_f32 v[116:117], v[120:121], v[190:191], v[116:117]
	v_mov_b32_e32 v149, v191
	v_mov_b32_e32 v113, v121
	v_mov_b32_e32 v191, v157
	v_mov_b32_e32 v126, v120
	v_mov_b32_e32 v148, v156
	v_pk_mul_f32 v[112:113], v[112:113], v[190:191]
	v_mov_b32_e32 v121, v115
	v_pk_fma_f32 v[112:113], v[126:127], v[148:149], v[112:113] neg_lo:[0,0,1] neg_hi:[0,0,1]
	v_mov_b32_e32 v127, v131
	v_mov_b32_e32 v115, v119
	v_mov_b32_e32 v131, v151
	v_mov_b32_e32 v120, v118
	v_mov_b32_e32 v126, v150
	v_pk_mul_f32 v[114:115], v[114:115], v[130:131]
	v_pk_mul_f32 v[120:121], v[120:121], v[126:127]
	v_pk_mul_f32 v[114:115], v[114:115], v[206:207] op_sel_hi:[1,0]
	v_pk_mul_f32 v[120:121], v[120:121], v[206:207] op_sel_hi:[1,0]
	v_pk_mul_f32 v[118:119], v[114:115], v[144:145]
	v_mov_b32_e32 v148, v120
	v_pk_fma_f32 v[118:119], v[120:121], v[188:189], v[118:119]
	v_cvt_pk_bf16_f32 v112, v112, v113
	v_mul_f32_e32 v113, v109, v109
	v_mul_f32_e32 v120, v111, v111
	v_fmac_f32_e32 v113, v108, v108
	v_fmac_f32_e32 v120, v110, v110
	v_mov_b32_e32 v149, v115
	v_mov_b32_e32 v115, v121
	v_add_f32_e32 v113, v113, v120
	v_mul_f32_e32 v120, v105, v105
	v_mul_f32_e32 v121, v107, v107
	v_fmac_f32_e32 v120, v104, v104
	v_fmac_f32_e32 v121, v106, v106
	v_add_f32_e32 v120, v120, v121
	v_add_f32_e32 v113, v113, v120
	v_mul_f32_e32 v120, v101, v101
	v_mul_f32_e32 v121, v103, v103
	v_fmac_f32_e32 v120, v100, v100
	v_fmac_f32_e32 v121, v102, v102
	v_add_f32_e32 v120, v120, v121
	v_add_f32_e32 v113, v113, v120
	v_mul_f32_e32 v120, v97, v97
	v_mul_f32_e32 v121, v99, v99
	v_fmac_f32_e32 v120, v96, v96
	v_fmac_f32_e32 v121, v98, v98
	v_add_f32_e32 v120, v120, v121
	v_add_f32_e32 v120, v113, v120
	ds_bpermute_b32 v121, v179, v120
	v_mov_b32_e32 v151, v189
	v_mov_b32_e32 v189, v145
	v_mov_b32_e32 v150, v144
	v_pk_mul_f32 v[114:115], v[114:115], v[188:189]
	v_mov_b32_e32 v144, 0
	v_pk_fma_f32 v[114:115], v[148:149], v[150:151], v[114:115] neg_lo:[0,0,1] neg_hi:[0,0,1]
	v_mov_b32_e32 v148, 0
	v_cvt_pk_bf16_f32 v113, v114, v115
	v_cvt_pk_bf16_f32 v114, v116, v117
	v_cvt_pk_bf16_f32 v115, v118, v119
	global_store_dwordx4 v[208:209], v[112:115], off offset:64
	v_mov_b32_e32 v149, 1.0
	v_mov_b32_e32 v118, 1.0
	s_waitcnt lgkmcnt(0)
	v_add_f32_e32 v113, v120, v121
	ds_bpermute_b32 v145, v204, v113
	v_mov_b32_e32 v112, 1.0
	v_mov_b32_e32 v114, 1.0
	v_mov_b32_e32 v115, 0
	v_mov_b32_e32 v116, 0
	v_mov_b32_e32 v117, 1.0
	v_mov_b32_e32 v119, 0
	s_cbranch_vccnz .LBB0_365
	s_waitcnt vmcnt(6)
	v_lshlrev_b32_e32 v168, 3, v172
	v_lshl_add_u64 v[118:119], v[180:181], 0, v[168:169]
	v_mov_b32_e32 v114, v242
	v_mov_b32_e32 v115, v243
	v_mov_b32_e32 v116, v244
	v_mov_b32_e32 v117, v245
	s_nop 0
	v_mov_b32_e32 v118, v248
	v_mov_b32_e32 v119, v249
	v_mov_b32_e32 v120, v250
	v_mov_b32_e32 v121, v251
	v_mov_b32_e32 v148, v115
	v_mov_b32_e32 v149, v116
	v_mov_b32_e32 v115, v117
	v_mov_b32_e32 v116, v119
	v_mov_b32_e32 v117, v120
	v_mov_b32_e32 v119, v121
	v_mov_b32_e32 v248, s64
	v_lshl_add_u32 v248, v248, 6, s51
	v_ashrrev_i32_e32 v249, 31, v248
	v_lshl_add_u64 v[248:249], v[248:249], 3, v[180:181]
	global_load_dwordx4 v[242:245], v[248:249], off offset:16
	global_load_dwordx4 v[248:251], v[248:249], off
; __device__ __forceinline__ unsigned cvtpk(float lo, float hi) { f32x2 v = {lo, hi}; bf16x2_t b = __builtin_convertvector(v, bf16x2_t); return __builtin_bit_cast(unsigned, b); }
;     __device__ __forceinline__ void operator()(const f32x4 (&acc)[2][2][4][2], const pg8::Unit& u, int wr, int wc, int fr, int fq) const {
;     ...
; #pragma unroll
;                 for (int m = 0; m < 4; ++m) {
;                     const int t = 256 * u.pm + 128 * ai + 64 * wr + 16 * m + fr;
;                     float ss = 0.f;
; #pragma unroll
;                     for (int bj = 0; bj < 2; ++bj)
; #pragma unroll
;                         for (int n = 0; n < 2; ++n) { const f32x4 v = acc[ai][bj][m][n]; ss += (v[0] * v[0] + v[1] * v[1]) + (v[2] * v[2] + v[3] * v[3]); }
;                     ss += __shfl_xor(ss, 16); ss += __shfl_xor(ss, 32);
;                     const float rstd = __builtin_amdgcn_rsqf(ss * (1.0f / 64.0f) + EPS) * osc;
;                     f32x4 cc0, cc1;
;                     if (kind == 0) { const f32x4* tp = (const f32x4*)(tab + (16 * m + fr) * 16 + 4 * fq); cc0 = tp[0]; cc1 = tp[1]; }
;                     else { cc0 = (f32x4){1.f, 0.f, 1.f, 0.f}; cc1 = cc0; }
;                     bf16_t* rowp = dst + (size_t)(rowoff + t) * 1024 + G * 64 + 8 * fq;
; #pragma unroll
;                     for (int bj = 0; bj < 2; ++bj) {
;                         const f32x4 x1 = acc[ai][bj][m][0] * g[bj][0] * rstd, x2 = acc[ai][bj][m][1] * g[bj][1] * rstd;
;                         const f32x4 ca = bj == 0 ? cr0 : cc0, cb = bj == 0 ? cr1 : cc1;
;                         const float co[4] = {ca[0], ca[2], cb[0], cb[2]}, si[4] = {ca[1], ca[3], cb[1], cb[3]};
;                         float o1[4], o2[4];
; #pragma unroll
;                         for (int e = 0; e < 4; ++e) { o1[e] = x1[e] * co[e] - x2[e] * si[e]; o2[e] = x2[e] * co[e] + x1[e] * si[e]; }
;                         u32x4 w; w.x = cvtpk(o1[0], o1[1]); w.y = cvtpk(o1[2], o1[3]); w.z = cvtpk(o2[0], o2[1]); w.w = cvtpk(o2[2], o2[3]);
;                         *(u32x4*)(rowp + 32 * bj) = w;
.LBB0_365:
	s_waitcnt lgkmcnt(0)
	v_add_f32_e32 v113, v113, v145
	v_fmamk_f32 v113, v113, 0x3c800000, v202
	v_rsq_f32_e32 v113, v113
	v_mov_b32_e32 v157, v105
	v_mov_b32_e32 v105, v109
	v_mov_b32_e32 v156, v108
	v_mul_f32_e32 v150, s6, v113
	v_pk_mul_f32 v[104:105], v[104:105], v[132:133]
	v_pk_mul_f32 v[156:157], v[156:157], v[142:143]
	v_pk_mul_f32 v[104:105], v[104:105], v[150:151] op_sel_hi:[1,0]
	v_pk_mul_f32 v[108:109], v[156:157], v[150:151] op_sel_hi:[1,0]
	v_pk_mul_f32 v[156:157], v[140:141], v[104:105]
	v_mov_b32_e32 v188, v108
	v_pk_fma_f32 v[156:157], v[184:185], v[108:109], v[156:157]
	v_mov_b32_e32 v189, v105
	v_mov_b32_e32 v105, v109
	v_mov_b32_e32 v108, v110
	v_mov_b32_e32 v109, v107
	v_mov_b32_e32 v107, v111
	v_pk_mul_f32 v[108:109], v[108:109], v[124:125]
	v_pk_mul_f32 v[106:107], v[106:107], v[134:135]
	v_pk_mul_f32 v[104:105], v[158:159], v[104:105]
	v_pk_mul_f32 v[108:109], v[108:109], v[150:151] op_sel_hi:[1,0]
	v_pk_mul_f32 v[106:107], v[106:107], v[150:151] op_sel_hi:[1,0]
	v_add3_u32 v120, v205, s66, 16
	v_pk_fma_f32 v[104:105], v[152:153], v[188:189], v[104:105] neg_lo:[0,0,1] neg_hi:[0,0,1]
	v_pk_mul_f32 v[110:111], v[136:137], v[106:107]
	v_mov_b32_e32 v189, v107
	v_mov_b32_e32 v107, v109
	v_ashrrev_i32_e32 v121, 31, v120
	v_mov_b32_e32 v188, v108
	v_pk_mul_f32 v[106:107], v[186:187], v[106:107]
	v_lshlrev_b64 v[120:121], 11, v[120:121]
	v_pk_fma_f32 v[110:111], v[182:183], v[108:109], v[110:111]
	v_pk_fma_f32 v[106:107], v[154:155], v[188:189], v[106:107] neg_lo:[0,0,1] neg_hi:[0,0,1]
	v_lshl_add_u64 v[120:121], v[138:139], 0, v[120:121]
	v_cvt_pk_bf16_f32 v104, v104, v105
	v_cvt_pk_bf16_f32 v105, v106, v107
	v_cvt_pk_bf16_f32 v106, v156, v157
	v_cvt_pk_bf16_f32 v107, v110, v111
	global_store_dwordx4 v[120:121], v[104:107], off
	v_mov_b32_e32 v109, v117
	v_mov_b32_e32 v108, v118
	v_mov_b32_e32 v105, v97
	v_mov_b32_e32 v97, v101
	v_mov_b32_e32 v104, v100
	v_pk_mul_f32 v[96:97], v[96:97], v[128:129]
	v_pk_mul_f32 v[104:105], v[104:105], v[122:123]
	v_pk_mul_f32 v[96:97], v[96:97], v[150:151] op_sel_hi:[1,0]
	v_pk_mul_f32 v[100:101], v[104:105], v[150:151] op_sel_hi:[1,0]
	v_pk_mul_f32 v[104:105], v[96:97], v[118:119]
	v_mov_b32_e32 v107, v97
	v_pk_fma_f32 v[104:105], v[100:101], v[116:117], v[104:105]
	v_mov_b32_e32 v97, v101
	v_mov_b32_e32 v101, v99
	v_mov_b32_e32 v99, v103
	v_mov_b32_e32 v106, v100
	v_mov_b32_e32 v117, v119
	v_mov_b32_e32 v100, v102
	v_pk_mul_f32 v[98:99], v[98:99], v[130:131]
	v_pk_mul_f32 v[96:97], v[96:97], v[116:117]
	v_pk_mul_f32 v[100:101], v[100:101], v[126:127]
	v_pk_mul_f32 v[98:99], v[98:99], v[150:151] op_sel_hi:[1,0]
	v_pk_fma_f32 v[96:97], v[106:107], v[108:109], v[96:97] neg_lo:[0,0,1] neg_hi:[0,0,1]
	v_pk_mul_f32 v[100:101], v[100:101], v[150:151] op_sel_hi:[1,0]
	v_pk_mul_f32 v[102:103], v[98:99], v[114:115]
	v_mov_b32_e32 v106, v100
	v_pk_fma_f32 v[102:103], v[100:101], v[148:149], v[102:103]
	v_cvt_pk_bf16_f32 v96, v96, v97
	v_mul_f32_e32 v97, v93, v93
	v_mul_f32_e32 v100, v95, v95
	v_fmac_f32_e32 v97, v92, v92
	v_fmac_f32_e32 v100, v94, v94
	v_mov_b32_e32 v107, v99
	v_mov_b32_e32 v99, v101
	v_add_f32_e32 v97, v97, v100
	v_mul_f32_e32 v100, v89, v89
	v_mul_f32_e32 v101, v91, v91
	v_fmac_f32_e32 v100, v88, v88
	v_fmac_f32_e32 v101, v90, v90
	v_add_f32_e32 v100, v100, v101
	v_add_f32_e32 v97, v97, v100
	v_mul_f32_e32 v100, v85, v85
	v_mul_f32_e32 v101, v87, v87
	v_fmac_f32_e32 v100, v84, v84
	v_fmac_f32_e32 v101, v86, v86
	v_add_f32_e32 v100, v100, v101
	v_add_f32_e32 v97, v97, v100
	v_mul_f32_e32 v100, v81, v81
	v_mul_f32_e32 v101, v83, v83
	v_fmac_f32_e32 v100, v80, v80
	v_fmac_f32_e32 v101, v82, v82
	v_add_f32_e32 v100, v100, v101
	v_add_f32_e32 v100, v97, v100
	ds_bpermute_b32 v101, v179, v100
	v_mov_b32_e32 v109, v149
	v_mov_b32_e32 v149, v115
	v_mov_b32_e32 v108, v114
	v_pk_mul_f32 v[98:99], v[98:99], v[148:149]
	s_and_b64 vcc, exec, s[4:5]
	v_pk_fma_f32 v[98:99], v[106:107], v[108:109], v[98:99] neg_lo:[0,0,1] neg_hi:[0,0,1]
	v_mov_b32_e32 v145, 1.0
	v_cvt_pk_bf16_f32 v97, v98, v99
	v_cvt_pk_bf16_f32 v99, v102, v103
	s_waitcnt lgkmcnt(0)
	v_add_f32_e32 v102, v100, v101
	ds_bpermute_b32 v103, v204, v102
	v_cvt_pk_bf16_f32 v98, v104, v105
	global_store_dwordx4 v[120:121], v[96:99], off offset:64
	v_mov_b32_e32 v113, 0
	v_mov_b32_e32 v100, 0
	v_mov_b32_e32 v96, 1.0
	v_mov_b32_e32 v101, 1.0
	v_mov_b32_e32 v97, 0
	s_cbranch_vccnz .LBB0_367
	s_waitcnt vmcnt(8)
	v_lshlrev_b32_e32 v168, 3, v172
	v_lshl_add_u64 v[96:97], v[180:181], 0, v[168:169]
	v_lshl_add_u64 v[98:99], v[96:97], 0, s[18:19]
	v_add_co_u32_e32 v96, vcc, 0x1000, v96
	v_mov_b32_e32 v112, v216
	v_mov_b32_e32 v113, v217
	v_mov_b32_e32 v114, v218
	v_mov_b32_e32 v115, v219
	s_nop 0
	v_addc_co_u32_e32 v97, vcc, 0, v97, vcc
	v_mov_b32_e32 v96, v230
	v_mov_b32_e32 v97, v231
	v_mov_b32_e32 v98, v232
	v_mov_b32_e32 v99, v233
	v_mov_b32_e32 v144, v113
	v_mov_b32_e32 v145, v114
	v_mov_b32_e32 v113, v115
	v_mov_b32_e32 v100, v97
	v_mov_b32_e32 v101, v98
	v_mov_b32_e32 v97, v99
	v_lshlrev_b32_e32 v230, 3, v172
	v_mov_b32_e32 v231, 0
	v_lshl_add_u64 v[230:231], v[180:181], 0, v[230:231]
	global_load_dwordx4 v[216:219], v[230:231], off offset:16
	global_load_dwordx4 v[230:233], v[230:231], off
; __device__ __forceinline__ unsigned cvtpk(float lo, float hi) { f32x2 v = {lo, hi}; bf16x2_t b = __builtin_convertvector(v, bf16x2_t); return __builtin_bit_cast(unsigned, b); }
;     __device__ __forceinline__ void operator()(const f32x4 (&acc)[2][2][4][2], const pg8::Unit& u, int wr, int wc, int fr, int fq) const {
;     ...
; #pragma unroll
;                 for (int m = 0; m < 4; ++m) {
;                     const int t = 256 * u.pm + 128 * ai + 64 * wr + 16 * m + fr;
;                     float ss = 0.f;
; #pragma unroll
;                     for (int bj = 0; bj < 2; ++bj)
; #pragma unroll
;                         for (int n = 0; n < 2; ++n) { const f32x4 v = acc[ai][bj][m][n]; ss += (v[0] * v[0] + v[1] * v[1]) + (v[2] * v[2] + v[3] * v[3]); }
;                     ss += __shfl_xor(ss, 16); ss += __shfl_xor(ss, 32);
;                     const float rstd = __builtin_amdgcn_rsqf(ss * (1.0f / 64.0f) + EPS) * osc;
;                     f32x4 cc0, cc1;
;                     if (kind == 0) { const f32x4* tp = (const f32x4*)(tab + (16 * m + fr) * 16 + 4 * fq); cc0 = tp[0]; cc1 = tp[1]; }
;                     else { cc0 = (f32x4){1.f, 0.f, 1.f, 0.f}; cc1 = cc0; }
;                     bf16_t* rowp = dst + (size_t)(rowoff + t) * 1024 + G * 64 + 8 * fq;
; #pragma unroll
;                     for (int bj = 0; bj < 2; ++bj) {
;                         const f32x4 x1 = acc[ai][bj][m][0] * g[bj][0] * rstd, x2 = acc[ai][bj][m][1] * g[bj][1] * rstd;
;                         const f32x4 ca = bj == 0 ? cr0 : cc0, cb = bj == 0 ? cr1 : cc1;
;                         const float co[4] = {ca[0], ca[2], cb[0], cb[2]}, si[4] = {ca[1], ca[3], cb[1], cb[3]};
;                         float o1[4], o2[4];
; #pragma unroll
;                         for (int e = 0; e < 4; ++e) { o1[e] = x1[e] * co[e] - x2[e] * si[e]; o2[e] = x2[e] * co[e] + x1[e] * si[e]; }
;                         u32x4 w; w.x = cvtpk(o1[0], o1[1]); w.y = cvtpk(o1[2], o1[3]); w.z = cvtpk(o2[0], o2[1]); w.w = cvtpk(o2[2], o2[3]);
;                         *(u32x4*)(rowp + 32 * bj) = w;
.LBB0_367:
	s_waitcnt lgkmcnt(0)
	v_add_f32_e32 v98, v102, v103
	v_fmamk_f32 v98, v98, 0x3c800000, v202
	v_rsq_f32_e32 v102, v98
	v_mov_b32_e32 v105, v89
	v_mov_b32_e32 v89, v93
	v_mov_b32_e32 v104, v92
	v_mul_f32_e32 v102, s6, v102
	v_pk_mul_f32 v[88:89], v[88:89], v[132:133]
	v_pk_mul_f32 v[104:105], v[104:105], v[142:143]
	v_pk_mul_f32 v[88:89], v[88:89], v[102:103] op_sel_hi:[1,0]
	v_pk_mul_f32 v[92:93], v[104:105], v[102:103] op_sel_hi:[1,0]
	v_pk_mul_f32 v[104:105], v[140:141], v[88:89]
	v_mov_b32_e32 v106, v92
	v_pk_fma_f32 v[104:105], v[184:185], v[92:93], v[104:105]
	v_mov_b32_e32 v107, v89
	v_mov_b32_e32 v89, v93
	v_mov_b32_e32 v92, v94
	v_mov_b32_e32 v93, v91
	v_mov_b32_e32 v91, v95
	v_pk_mul_f32 v[92:93], v[92:93], v[124:125]
	v_pk_mul_f32 v[90:91], v[90:91], v[134:135]
	v_pk_mul_f32 v[88:89], v[158:159], v[88:89]
	v_pk_mul_f32 v[92:93], v[92:93], v[102:103] op_sel_hi:[1,0]
	v_pk_mul_f32 v[90:91], v[90:91], v[102:103] op_sel_hi:[1,0]
	v_add3_u32 v98, v205, s66, 32
	v_pk_fma_f32 v[88:89], v[152:153], v[106:107], v[88:89] neg_lo:[0,0,1] neg_hi:[0,0,1]
	v_pk_mul_f32 v[94:95], v[136:137], v[90:91]
	v_mov_b32_e32 v107, v91
	v_mov_b32_e32 v91, v93
	v_ashrrev_i32_e32 v99, 31, v98
	v_mov_b32_e32 v106, v92
	v_pk_mul_f32 v[90:91], v[186:187], v[90:91]
	v_lshlrev_b64 v[98:99], 11, v[98:99]
	v_pk_fma_f32 v[94:95], v[182:183], v[92:93], v[94:95]
	v_pk_fma_f32 v[90:91], v[154:155], v[106:107], v[90:91] neg_lo:[0,0,1] neg_hi:[0,0,1]
	v_lshl_add_u64 v[98:99], v[138:139], 0, v[98:99]
	v_cvt_pk_bf16_f32 v88, v88, v89
	v_cvt_pk_bf16_f32 v89, v90, v91
	v_cvt_pk_bf16_f32 v90, v104, v105
	v_cvt_pk_bf16_f32 v91, v94, v95
	global_store_dwordx4 v[98:99], v[88:91], off
	v_mov_b32_e32 v93, v101
	v_mov_b32_e32 v92, v96
	v_mov_b32_e32 v89, v81
	v_mov_b32_e32 v81, v85
	v_mov_b32_e32 v88, v84
	v_pk_mul_f32 v[80:81], v[80:81], v[128:129]
	v_pk_mul_f32 v[88:89], v[88:89], v[122:123]
	v_pk_mul_f32 v[80:81], v[80:81], v[102:103] op_sel_hi:[1,0]
	v_pk_mul_f32 v[84:85], v[88:89], v[102:103] op_sel_hi:[1,0]
	v_pk_mul_f32 v[88:89], v[80:81], v[96:97]
	v_mov_b32_e32 v91, v81
	v_pk_fma_f32 v[88:89], v[84:85], v[100:101], v[88:89]
	v_mov_b32_e32 v81, v85
	v_mov_b32_e32 v85, v83
	v_mov_b32_e32 v83, v87
	v_mov_b32_e32 v90, v84
	v_mov_b32_e32 v101, v97
	v_mov_b32_e32 v84, v86
	v_pk_mul_f32 v[82:83], v[82:83], v[130:131]
	v_pk_mul_f32 v[80:81], v[80:81], v[100:101]
	v_pk_mul_f32 v[84:85], v[84:85], v[126:127]
	v_pk_mul_f32 v[82:83], v[82:83], v[102:103] op_sel_hi:[1,0]
	v_pk_fma_f32 v[80:81], v[90:91], v[92:93], v[80:81] neg_lo:[0,0,1] neg_hi:[0,0,1]
	v_pk_mul_f32 v[84:85], v[84:85], v[102:103] op_sel_hi:[1,0]
	v_pk_mul_f32 v[86:87], v[82:83], v[112:113]
	v_mov_b32_e32 v90, v84
	v_pk_fma_f32 v[86:87], v[84:85], v[144:145], v[86:87]
	v_cvt_pk_bf16_f32 v80, v80, v81
	v_mul_f32_e32 v81, v77, v77
	v_mul_f32_e32 v84, v79, v79
	v_fmac_f32_e32 v81, v76, v76
	v_fmac_f32_e32 v84, v78, v78
	v_mov_b32_e32 v91, v83
	v_mov_b32_e32 v83, v85
	v_add_f32_e32 v81, v81, v84
	v_mul_f32_e32 v84, v73, v73
	v_mul_f32_e32 v85, v75, v75
	v_fmac_f32_e32 v84, v72, v72
	v_fmac_f32_e32 v85, v74, v74
	v_add_f32_e32 v84, v84, v85
	v_add_f32_e32 v81, v81, v84
	v_mul_f32_e32 v84, v69, v69
	v_mul_f32_e32 v85, v71, v71
	v_fmac_f32_e32 v84, v68, v68
	v_fmac_f32_e32 v85, v70, v70
	v_add_f32_e32 v84, v84, v85
	v_add_f32_e32 v81, v81, v84
	v_mul_f32_e32 v84, v65, v65
	v_mul_f32_e32 v85, v67, v67
	v_fmac_f32_e32 v84, v64, v64
	v_fmac_f32_e32 v85, v66, v66
	v_add_f32_e32 v84, v84, v85
	v_add_f32_e32 v84, v81, v84
	ds_bpermute_b32 v85, v179, v84
	v_mov_b32_e32 v93, v145
	v_mov_b32_e32 v145, v113
	v_mov_b32_e32 v92, v112
	v_pk_mul_f32 v[82:83], v[82:83], v[144:145]
	s_and_b64 vcc, exec, s[4:5]
	v_pk_fma_f32 v[82:83], v[90:91], v[92:93], v[82:83] neg_lo:[0,0,1] neg_hi:[0,0,1]
	v_mov_b32_e32 v90, 0
	v_cvt_pk_bf16_f32 v81, v82, v83
	v_cvt_pk_bf16_f32 v82, v88, v89
	v_cvt_pk_bf16_f32 v83, v86, v87
	global_store_dwordx4 v[98:99], v[80:83], off offset:64
	v_mov_b32_e32 v92, 0
	v_mov_b32_e32 v93, 1.0
	s_waitcnt lgkmcnt(0)
	v_add_f32_e32 v81, v84, v85
	ds_bpermute_b32 v91, v204, v81
	v_mov_b32_e32 v80, 1.0
	v_mov_b32_e32 v82, 1.0
	v_mov_b32_e32 v83, 0
	v_mov_b32_e32 v86, 1.0
	v_mov_b32_e32 v84, 0
	v_mov_b32_e32 v85, 1.0
	v_mov_b32_e32 v87, 0
	s_cbranch_vccnz .LBB0_369
	s_waitcnt vmcnt(10)
	v_lshlrev_b32_e32 v168, 3, v172
	v_lshl_add_u64 v[86:87], v[180:181], 0, v[168:169]
	v_lshl_add_u64 v[82:83], v[86:87], 0, s[30:31]
	v_add_co_u32_e32 v86, vcc, 0x1000, v86
	v_mov_b32_e32 v82, v234
	v_mov_b32_e32 v83, v235
	v_mov_b32_e32 v84, v236
	v_mov_b32_e32 v85, v237
	s_nop 0
	v_addc_co_u32_e32 v87, vcc, 0, v87, vcc
	v_mov_b32_e32 v86, v238
	v_mov_b32_e32 v87, v239
	v_mov_b32_e32 v88, v240
	v_mov_b32_e32 v89, v241
	v_mov_b32_e32 v92, v83
	v_mov_b32_e32 v93, v84
	v_mov_b32_e32 v83, v85
	v_mov_b32_e32 v84, v87
	v_mov_b32_e32 v85, v88
	v_mov_b32_e32 v87, v89
	v_lshlrev_b32_e32 v238, 3, v172
	v_mov_b32_e32 v239, 0
	v_lshl_add_u64 v[238:239], v[180:181], 0, v[238:239]
	global_load_dwordx4 v[234:237], v[238:239], off offset:2064
	global_load_dwordx4 v[238:241], v[238:239], off offset:2048
; __device__ __forceinline__ unsigned cvtpk(float lo, float hi) { f32x2 v = {lo, hi}; bf16x2_t b = __builtin_convertvector(v, bf16x2_t); return __builtin_bit_cast(unsigned, b); }
;     __device__ __forceinline__ void operator()(const f32x4 (&acc)[2][2][4][2], const pg8::Unit& u, int wr, int wc, int fr, int fq) const {
;     ...
; #pragma unroll
;                 for (int m = 0; m < 4; ++m) {
;                     const int t = 256 * u.pm + 128 * ai + 64 * wr + 16 * m + fr;
;                     float ss = 0.f;
; #pragma unroll
;                     for (int bj = 0; bj < 2; ++bj)
; #pragma unroll
;                         for (int n = 0; n < 2; ++n) { const f32x4 v = acc[ai][bj][m][n]; ss += (v[0] * v[0] + v[1] * v[1]) + (v[2] * v[2] + v[3] * v[3]); }
;                     ss += __shfl_xor(ss, 16); ss += __shfl_xor(ss, 32);
;                     const float rstd = __builtin_amdgcn_rsqf(ss * (1.0f / 64.0f) + EPS) * osc;
;                     f32x4 cc0, cc1;
;                     if (kind == 0) { const f32x4* tp = (const f32x4*)(tab + (16 * m + fr) * 16 + 4 * fq); cc0 = tp[0]; cc1 = tp[1]; }
;                     else { cc0 = (f32x4){1.f, 0.f, 1.f, 0.f}; cc1 = cc0; }
;                     bf16_t* rowp = dst + (size_t)(rowoff + t) * 1024 + G * 64 + 8 * fq;
; #pragma unroll
;                     for (int bj = 0; bj < 2; ++bj) {
;                         const f32x4 x1 = acc[ai][bj][m][0] * g[bj][0] * rstd, x2 = acc[ai][bj][m][1] * g[bj][1] * rstd;
;                         const f32x4 ca = bj == 0 ? cr0 : cc0, cb = bj == 0 ? cr1 : cc1;
;                         const float co[4] = {ca[0], ca[2], cb[0], cb[2]}, si[4] = {ca[1], ca[3], cb[1], cb[3]};
;                         float o1[4], o2[4];
; #pragma unroll
;                         for (int e = 0; e < 4; ++e) { o1[e] = x1[e] * co[e] - x2[e] * si[e]; o2[e] = x2[e] * co[e] + x1[e] * si[e]; }
;                         u32x4 w; w.x = cvtpk(o1[0], o1[1]); w.y = cvtpk(o1[2], o1[3]); w.z = cvtpk(o2[0], o2[1]); w.w = cvtpk(o2[2], o2[3]);
;                         *(u32x4*)(rowp + 32 * bj) = w;
.LBB0_369:
	s_waitcnt lgkmcnt(0)
	v_add_f32_e32 v81, v81, v91
	v_fmamk_f32 v81, v81, 0x3c800000, v202
	v_rsq_f32_e32 v81, v81
	v_mov_b32_e32 v97, v73
	v_mov_b32_e32 v73, v77
	v_mov_b32_e32 v96, v76
	v_mul_f32_e32 v94, s6, v81
	v_pk_mul_f32 v[72:73], v[72:73], v[132:133]
	v_pk_mul_f32 v[96:97], v[96:97], v[142:143]
	v_pk_mul_f32 v[72:73], v[72:73], v[94:95] op_sel_hi:[1,0]
	v_pk_mul_f32 v[76:77], v[96:97], v[94:95] op_sel_hi:[1,0]
	v_pk_mul_f32 v[96:97], v[140:141], v[72:73]
	v_mov_b32_e32 v98, v76
	v_pk_fma_f32 v[96:97], v[184:185], v[76:77], v[96:97]
	v_mov_b32_e32 v99, v73
	v_mov_b32_e32 v73, v77
	v_mov_b32_e32 v76, v78
	v_mov_b32_e32 v77, v75
	v_mov_b32_e32 v75, v79
	v_pk_mul_f32 v[76:77], v[76:77], v[124:125]
	v_pk_mul_f32 v[74:75], v[74:75], v[134:135]
	v_pk_mul_f32 v[72:73], v[158:159], v[72:73]
	v_pk_mul_f32 v[76:77], v[76:77], v[94:95] op_sel_hi:[1,0]
	v_pk_mul_f32 v[74:75], v[74:75], v[94:95] op_sel_hi:[1,0]
	v_add3_u32 v88, v205, s66, 48
	v_pk_fma_f32 v[72:73], v[152:153], v[98:99], v[72:73] neg_lo:[0,0,1] neg_hi:[0,0,1]
	v_pk_mul_f32 v[78:79], v[136:137], v[74:75]
	v_mov_b32_e32 v99, v75
	v_mov_b32_e32 v75, v77
	v_ashrrev_i32_e32 v89, 31, v88
	v_mov_b32_e32 v98, v76
	v_pk_mul_f32 v[74:75], v[186:187], v[74:75]
	v_lshlrev_b64 v[88:89], 11, v[88:89]
	v_pk_fma_f32 v[78:79], v[182:183], v[76:77], v[78:79]
	v_pk_fma_f32 v[74:75], v[154:155], v[98:99], v[74:75] neg_lo:[0,0,1] neg_hi:[0,0,1]
	v_lshl_add_u64 v[88:89], v[138:139], 0, v[88:89]
	v_cvt_pk_bf16_f32 v72, v72, v73
	v_cvt_pk_bf16_f32 v73, v74, v75
	v_cvt_pk_bf16_f32 v74, v96, v97
	v_cvt_pk_bf16_f32 v75, v78, v79
	global_store_dwordx4 v[88:89], v[72:75], off
	v_mov_b32_e32 v77, v85
	v_mov_b32_e32 v76, v86
	v_mov_b32_e32 v73, v65
	v_mov_b32_e32 v65, v69
	v_mov_b32_e32 v72, v68
	v_pk_mul_f32 v[64:65], v[64:65], v[128:129]
	v_pk_mul_f32 v[72:73], v[72:73], v[122:123]
	v_pk_mul_f32 v[64:65], v[64:65], v[94:95] op_sel_hi:[1,0]
	v_pk_mul_f32 v[68:69], v[72:73], v[94:95] op_sel_hi:[1,0]
	v_pk_mul_f32 v[72:73], v[64:65], v[86:87]
	v_mov_b32_e32 v75, v65
	v_pk_fma_f32 v[72:73], v[68:69], v[84:85], v[72:73]
	v_mov_b32_e32 v65, v69
	v_mov_b32_e32 v69, v67
	v_mov_b32_e32 v67, v71
	v_mov_b32_e32 v74, v68
	v_mov_b32_e32 v68, v70
	v_pk_mul_f32 v[66:67], v[66:67], v[130:131]
	v_mov_b32_e32 v85, v87
	v_pk_mul_f32 v[68:69], v[68:69], v[126:127]
	v_pk_mul_f32 v[66:67], v[66:67], v[94:95] op_sel_hi:[1,0]
	v_pk_mul_f32 v[64:65], v[64:65], v[84:85]
	v_pk_mul_f32 v[68:69], v[68:69], v[94:95] op_sel_hi:[1,0]
	v_pk_mul_f32 v[70:71], v[66:67], v[82:83]
	v_pk_fma_f32 v[64:65], v[74:75], v[76:77], v[64:65] neg_lo:[0,0,1] neg_hi:[0,0,1]
	v_pk_fma_f32 v[70:71], v[68:69], v[92:93], v[70:71]
	v_mov_b32_e32 v75, v67
	v_mov_b32_e32 v77, v93
	v_mov_b32_e32 v67, v69
	v_mov_b32_e32 v93, v83
	v_mov_b32_e32 v74, v68
	v_mov_b32_e32 v76, v82
	v_pk_mul_f32 v[66:67], v[66:67], v[92:93]
	v_cvt_pk_bf16_f32 v64, v64, v65
	v_pk_fma_f32 v[66:67], v[74:75], v[76:77], v[66:67] neg_lo:[0,0,1] neg_hi:[0,0,1]
	s_and_b64 vcc, exec, s[4:5]
	v_cvt_pk_bf16_f32 v65, v66, v67
	v_cvt_pk_bf16_f32 v66, v72, v73
	v_cvt_pk_bf16_f32 v67, v70, v71
	global_store_dwordx4 v[88:89], v[64:67], off offset:64
	v_mov_b32_e32 v91, 1.0
	v_mov_b32_e32 v81, 0
	v_mov_b32_e32 v64, 1.0
	v_mov_b32_e32 v76, 0
	v_mov_b32_e32 v77, 1.0
	v_mov_b32_e32 v65, 0
	s_cbranch_vccnz .LBB0_371
	s_waitcnt vmcnt(10)
	s_lshl_b32 s20, s64, 6
	s_add_i32 s20, s51, s20
	s_ashr_i32 s21, s20, 31
	v_lshl_add_u64 v[64:65], s[20:21], 3, v[180:181]
	v_mov_b32_e32 v80, v242
	v_mov_b32_e32 v81, v243
	v_mov_b32_e32 v82, v244
	v_mov_b32_e32 v83, v245
	s_nop 0
	v_mov_b32_e32 v64, v248
	v_mov_b32_e32 v65, v249
	v_mov_b32_e32 v66, v250
	v_mov_b32_e32 v67, v251
	v_mov_b32_e32 v90, v81
	v_mov_b32_e32 v91, v82
	v_mov_b32_e32 v81, v83
	v_mov_b32_e32 v76, v65
	v_mov_b32_e32 v77, v66
	v_mov_b32_e32 v65, v67
	v_lshlrev_b32_e32 v248, 3, v172
	v_mov_b32_e32 v249, 0
	v_lshl_add_u64 v[248:249], v[180:181], 0, v[248:249]
	v_lshl_add_u64 v[248:249], v[248:249], 0, s[18:19]
	global_load_dwordx4 v[242:245], v[248:249], off offset:16
	global_load_dwordx4 v[248:251], v[248:249], off
.LBB0_371:
	v_mul_f32_e32 v66, v61, v61
	v_mul_f32_e32 v67, v63, v63
	v_fmac_f32_e32 v66, v60, v60
	v_fmac_f32_e32 v67, v62, v62
	v_add_f32_e32 v66, v66, v67
	v_mul_f32_e32 v67, v57, v57
	v_mul_f32_e32 v68, v59, v59
	v_fmac_f32_e32 v67, v56, v56
	v_fmac_f32_e32 v68, v58, v58
	v_add_f32_e32 v67, v67, v68
	v_add_f32_e32 v66, v66, v67
	v_mul_f32_e32 v67, v53, v53
	v_mul_f32_e32 v68, v55, v55
	v_fmac_f32_e32 v67, v52, v52
	v_fmac_f32_e32 v68, v54, v54
	v_add_f32_e32 v67, v67, v68
	v_add_f32_e32 v66, v66, v67
	v_mul_f32_e32 v67, v49, v49
	v_mul_f32_e32 v68, v51, v51
	v_fmac_f32_e32 v67, v48, v48
	v_fmac_f32_e32 v68, v50, v50
	v_add_f32_e32 v67, v67, v68
	v_add_f32_e32 v66, v66, v67
	ds_bpermute_b32 v67, v179, v66
	v_mov_b32_e32 v78, 0
	s_and_b64 vcc, exec, s[4:5]
	v_mov_b32_e32 v68, 1.0
	v_mov_b32_e32 v82, 0
	s_waitcnt lgkmcnt(0)
	v_add_f32_e32 v67, v66, v67
	ds_bpermute_b32 v79, v204, v67
	v_mov_b32_e32 v66, 1.0
	v_mov_b32_e32 v83, 1.0
	v_mov_b32_e32 v69, 0
	v_mov_b32_e32 v72, 1.0
	v_mov_b32_e32 v70, 0
	v_mov_b32_e32 v71, 1.0
	v_mov_b32_e32 v73, 0
	s_cbranch_vccnz .LBB0_373
	s_waitcnt vmcnt(8)
	v_lshlrev_b32_e32 v168, 3, v172
	v_lshl_add_u64 v[72:73], v[180:181], 0, v[168:169]
	v_mov_b32_e32 v68, v216
	v_mov_b32_e32 v69, v217
	v_mov_b32_e32 v70, v218
	v_mov_b32_e32 v71, v219
	s_nop 0
	v_mov_b32_e32 v72, v230
	v_mov_b32_e32 v73, v231
	v_mov_b32_e32 v74, v232
	v_mov_b32_e32 v75, v233
	v_mov_b32_e32 v82, v69
	v_mov_b32_e32 v83, v70
	v_mov_b32_e32 v69, v71
	v_mov_b32_e32 v70, v73
	v_mov_b32_e32 v71, v74
	v_mov_b32_e32 v73, v75
	v_lshlrev_b32_e32 v230, 3, v172
	v_mov_b32_e32 v231, 0
	v_lshl_add_u64 v[230:231], v[180:181], 0, v[230:231]
	v_lshl_add_u64 v[230:231], v[230:231], 0, s[18:19]
	global_load_dwordx4 v[216:219], v[230:231], off offset:2064
	global_load_dwordx4 v[230:233], v[230:231], off offset:2048
; __device__ __forceinline__ unsigned cvtpk(float lo, float hi) { f32x2 v = {lo, hi}; bf16x2_t b = __builtin_convertvector(v, bf16x2_t); return __builtin_bit_cast(unsigned, b); }
;     __device__ __forceinline__ void operator()(const f32x4 (&acc)[2][2][4][2], const pg8::Unit& u, int wr, int wc, int fr, int fq) const {
;     ...
; #pragma unroll
;                 for (int m = 0; m < 4; ++m) {
;                     const int t = 256 * u.pm + 128 * ai + 64 * wr + 16 * m + fr;
;                     float ss = 0.f;
; #pragma unroll
;                     for (int bj = 0; bj < 2; ++bj)
; #pragma unroll
;                         for (int n = 0; n < 2; ++n) { const f32x4 v = acc[ai][bj][m][n]; ss += (v[0] * v[0] + v[1] * v[1]) + (v[2] * v[2] + v[3] * v[3]); }
;                     ss += __shfl_xor(ss, 16); ss += __shfl_xor(ss, 32);
;                     const float rstd = __builtin_amdgcn_rsqf(ss * (1.0f / 64.0f) + EPS) * osc;
;                     f32x4 cc0, cc1;
;                     if (kind == 0) { const f32x4* tp = (const f32x4*)(tab + (16 * m + fr) * 16 + 4 * fq); cc0 = tp[0]; cc1 = tp[1]; }
;                     else { cc0 = (f32x4){1.f, 0.f, 1.f, 0.f}; cc1 = cc0; }
;                     bf16_t* rowp = dst + (size_t)(rowoff + t) * 1024 + G * 64 + 8 * fq;
; #pragma unroll
;                     for (int bj = 0; bj < 2; ++bj) {
;                         const f32x4 x1 = acc[ai][bj][m][0] * g[bj][0] * rstd, x2 = acc[ai][bj][m][1] * g[bj][1] * rstd;
;                         const f32x4 ca = bj == 0 ? cr0 : cc0, cb = bj == 0 ? cr1 : cc1;
;                         const float co[4] = {ca[0], ca[2], cb[0], cb[2]}, si[4] = {ca[1], ca[3], cb[1], cb[3]};
;                         float o1[4], o2[4];
; #pragma unroll
;                         for (int e = 0; e < 4; ++e) { o1[e] = x1[e] * co[e] - x2[e] * si[e]; o2[e] = x2[e] * co[e] + x1[e] * si[e]; }
;                         u32x4 w; w.x = cvtpk(o1[0], o1[1]); w.y = cvtpk(o1[2], o1[3]); w.z = cvtpk(o2[0], o2[1]); w.w = cvtpk(o2[2], o2[3]);
;                         *(u32x4*)(rowp + 32 * bj) = w;
.LBB0_373:
	s_waitcnt lgkmcnt(0)
	v_add_f32_e32 v67, v67, v79
	v_fmamk_f32 v67, v67, 0x3c800000, v202
	v_rsq_f32_e32 v67, v67
	v_mov_b32_e32 v84, v60
	v_mov_b32_e32 v85, v57
	v_mov_b32_e32 v57, v61
	v_mul_f32_e32 v88, s6, v67
	v_pk_mul_f32 v[84:85], v[84:85], v[142:143]
	v_pk_mul_f32 v[56:57], v[56:57], v[132:133]
	v_pk_mul_f32 v[84:85], v[84:85], v[88:89] op_sel_hi:[1,0]
	v_pk_mul_f32 v[86:87], v[56:57], v[88:89] op_sel_hi:[1,0]
	v_mov_b32_e32 v60, v76
	v_pk_mul_f32 v[56:57], v[64:65], v[86:87]
	v_mov_b32_e32 v95, v87
	v_mov_b32_e32 v61, v65
	v_mov_b32_e32 v87, v85
	v_pk_fma_f32 v[92:93], v[76:77], v[84:85], v[56:57]
	v_mov_b32_e32 v94, v84
	v_pk_mul_f32 v[84:85], v[60:61], v[86:87]
	v_mov_b32_e32 v86, v62
	v_mov_b32_e32 v87, v59
	v_mov_b32_e32 v59, v63
	v_mov_b32_e32 v56, v64
	v_mov_b32_e32 v57, v77
	v_pk_mul_f32 v[86:87], v[86:87], v[124:125]
	v_pk_mul_f32 v[58:59], v[58:59], v[134:135]
	v_pk_fma_f32 v[84:85], v[56:57], v[94:95], v[84:85] neg_lo:[0,0,1] neg_hi:[0,0,1]
	v_pk_mul_f32 v[86:87], v[86:87], v[88:89] op_sel_hi:[1,0]
	v_pk_mul_f32 v[94:95], v[58:59], v[88:89] op_sel_hi:[1,0]
	v_add_u32_e32 v74, 0x80, v146
	v_pk_mul_f32 v[58:59], v[80:81], v[94:95]
	v_mov_b32_e32 v99, v95
	v_mov_b32_e32 v62, v90
	v_mov_b32_e32 v63, v81
	v_mov_b32_e32 v95, v87
	v_ashrrev_i32_e32 v75, 31, v74
	v_pk_fma_f32 v[96:97], v[90:91], v[86:87], v[58:59]
	v_mov_b32_e32 v58, v80
	v_mov_b32_e32 v59, v91
	v_mov_b32_e32 v98, v86
	v_pk_mul_f32 v[86:87], v[62:63], v[94:95]
	v_lshlrev_b64 v[74:75], 11, v[74:75]
	v_pk_fma_f32 v[86:87], v[58:59], v[98:99], v[86:87] neg_lo:[0,0,1] neg_hi:[0,0,1]
	v_lshl_add_u64 v[74:75], v[138:139], 0, v[74:75]
	v_cvt_pk_bf16_f32 v84, v84, v85
	v_cvt_pk_bf16_f32 v85, v86, v87
	v_cvt_pk_bf16_f32 v86, v92, v93
	v_cvt_pk_bf16_f32 v87, v96, v97
	global_store_dwordx4 v[74:75], v[84:87], off
	v_mov_b32_e32 v93, v71
	v_mov_b32_e32 v92, v72
	v_mov_b32_e32 v85, v49
	v_mov_b32_e32 v49, v53
	v_mov_b32_e32 v84, v52
	v_pk_mul_f32 v[48:49], v[48:49], v[128:129]
	v_pk_mul_f32 v[84:85], v[84:85], v[122:123]
	v_pk_mul_f32 v[48:49], v[48:49], v[88:89] op_sel_hi:[1,0]
	v_pk_mul_f32 v[52:53], v[84:85], v[88:89] op_sel_hi:[1,0]
	v_pk_mul_f32 v[84:85], v[48:49], v[72:73]
	v_mov_b32_e32 v87, v49
	v_pk_fma_f32 v[84:85], v[52:53], v[70:71], v[84:85]
	v_mov_b32_e32 v49, v53
	v_mov_b32_e32 v53, v51
	v_mov_b32_e32 v51, v55
	v_mov_b32_e32 v86, v52
	v_mov_b32_e32 v71, v73
	v_mov_b32_e32 v52, v54
	v_pk_mul_f32 v[50:51], v[50:51], v[130:131]
	v_pk_mul_f32 v[48:49], v[48:49], v[70:71]
	v_pk_mul_f32 v[52:53], v[52:53], v[126:127]
	v_pk_mul_f32 v[50:51], v[50:51], v[88:89] op_sel_hi:[1,0]
	v_pk_fma_f32 v[48:49], v[86:87], v[92:93], v[48:49] neg_lo:[0,0,1] neg_hi:[0,0,1]
	v_pk_mul_f32 v[52:53], v[52:53], v[88:89] op_sel_hi:[1,0]
	v_pk_mul_f32 v[54:55], v[50:51], v[68:69]
	v_mov_b32_e32 v70, v52
	v_pk_fma_f32 v[54:55], v[52:53], v[82:83], v[54:55]
	v_cvt_pk_bf16_f32 v48, v48, v49
	v_mul_f32_e32 v49, v45, v45
	v_mul_f32_e32 v52, v47, v47
	v_fmac_f32_e32 v49, v44, v44
	v_fmac_f32_e32 v52, v46, v46
	v_mov_b32_e32 v71, v51
	v_mov_b32_e32 v51, v53
	v_add_f32_e32 v49, v49, v52
	v_mul_f32_e32 v52, v41, v41
	v_mul_f32_e32 v53, v43, v43
	v_fmac_f32_e32 v52, v40, v40
	v_fmac_f32_e32 v53, v42, v42
	v_add_f32_e32 v52, v52, v53
	v_add_f32_e32 v49, v49, v52
	v_mul_f32_e32 v52, v37, v37
	v_mul_f32_e32 v53, v39, v39
	v_fmac_f32_e32 v52, v36, v36
	v_fmac_f32_e32 v53, v38, v38
	v_add_f32_e32 v52, v52, v53
	v_add_f32_e32 v49, v49, v52
	v_mul_f32_e32 v52, v33, v33
	v_mul_f32_e32 v53, v35, v35
	v_fmac_f32_e32 v52, v32, v32
	v_fmac_f32_e32 v53, v34, v34
	v_add_f32_e32 v52, v52, v53
	v_add_f32_e32 v52, v49, v52
	ds_bpermute_b32 v53, v179, v52
	v_mov_b32_e32 v73, v83
	v_mov_b32_e32 v83, v69
	v_mov_b32_e32 v72, v68
	v_pk_mul_f32 v[50:51], v[50:51], v[82:83]
	s_and_b64 vcc, exec, s[4:5]
	v_pk_fma_f32 v[50:51], v[70:71], v[72:73], v[50:51] neg_lo:[0,0,1] neg_hi:[0,0,1]
	v_mov_b32_e32 v79, 1.0
	v_cvt_pk_bf16_f32 v49, v50, v51
	v_cvt_pk_bf16_f32 v51, v54, v55
	s_waitcnt lgkmcnt(0)
	v_add_f32_e32 v54, v52, v53
	ds_bpermute_b32 v55, v204, v54
	v_cvt_pk_bf16_f32 v50, v84, v85
	global_store_dwordx4 v[74:75], v[48:51], off offset:64
	v_mov_b32_e32 v67, 0
	v_mov_b32_e32 v52, 0
	v_mov_b32_e32 v48, 1.0
	v_mov_b32_e32 v53, 1.0
	v_mov_b32_e32 v49, 0
	s_cbranch_vccnz .LBB0_375
	s_waitcnt vmcnt(8)
	v_lshlrev_b32_e32 v168, 3, v172
	v_lshl_add_u64 v[48:49], v[180:181], 0, v[168:169]
	v_mov_b32_e32 v66, v234
	v_mov_b32_e32 v67, v235
	v_mov_b32_e32 v68, v236
	v_mov_b32_e32 v69, v237
	s_nop 0
	v_mov_b32_e32 v48, v238
	v_mov_b32_e32 v49, v239
	v_mov_b32_e32 v50, v240
	v_mov_b32_e32 v51, v241
	v_mov_b32_e32 v78, v67
	v_mov_b32_e32 v79, v68
	v_mov_b32_e32 v67, v69
	v_mov_b32_e32 v52, v49
	v_mov_b32_e32 v53, v50
	v_mov_b32_e32 v49, v51
; __device__ __forceinline__ unsigned cvtpk(float lo, float hi) { f32x2 v = {lo, hi}; bf16x2_t b = __builtin_convertvector(v, bf16x2_t); return __builtin_bit_cast(unsigned, b); }
;     __device__ __forceinline__ void operator()(const f32x4 (&acc)[2][2][4][2], const pg8::Unit& u, int wr, int wc, int fr, int fq) const {
;     ...
; #pragma unroll
;                 for (int m = 0; m < 4; ++m) {
;                     const int t = 256 * u.pm + 128 * ai + 64 * wr + 16 * m + fr;
;                     float ss = 0.f;
; #pragma unroll
;                     for (int bj = 0; bj < 2; ++bj)
; #pragma unroll
;                         for (int n = 0; n < 2; ++n) { const f32x4 v = acc[ai][bj][m][n]; ss += (v[0] * v[0] + v[1] * v[1]) + (v[2] * v[2] + v[3] * v[3]); }
;                     ss += __shfl_xor(ss, 16); ss += __shfl_xor(ss, 32);
;                     const float rstd = __builtin_amdgcn_rsqf(ss * (1.0f / 64.0f) + EPS) * osc;
;                     f32x4 cc0, cc1;
;                     if (kind == 0) { const f32x4* tp = (const f32x4*)(tab + (16 * m + fr) * 16 + 4 * fq); cc0 = tp[0]; cc1 = tp[1]; }
;                     else { cc0 = (f32x4){1.f, 0.f, 1.f, 0.f}; cc1 = cc0; }
;                     bf16_t* rowp = dst + (size_t)(rowoff + t) * 1024 + G * 64 + 8 * fq;
; #pragma unroll
;                     for (int bj = 0; bj < 2; ++bj) {
;                         const f32x4 x1 = acc[ai][bj][m][0] * g[bj][0] * rstd, x2 = acc[ai][bj][m][1] * g[bj][1] * rstd;
;                         const f32x4 ca = bj == 0 ? cr0 : cc0, cb = bj == 0 ? cr1 : cc1;
;                         const float co[4] = {ca[0], ca[2], cb[0], cb[2]}, si[4] = {ca[1], ca[3], cb[1], cb[3]};
;                         float o1[4], o2[4];
; #pragma unroll
;                         for (int e = 0; e < 4; ++e) { o1[e] = x1[e] * co[e] - x2[e] * si[e]; o2[e] = x2[e] * co[e] + x1[e] * si[e]; }
;                         u32x4 w; w.x = cvtpk(o1[0], o1[1]); w.y = cvtpk(o1[2], o1[3]); w.z = cvtpk(o2[0], o2[1]); w.w = cvtpk(o2[2], o2[3]);
;                         *(u32x4*)(rowp + 32 * bj) = w;
.LBB0_375:
	s_waitcnt lgkmcnt(0)
	v_add_f32_e32 v50, v54, v55
	v_fmamk_f32 v50, v50, 0x3c800000, v202
	v_rsq_f32_e32 v54, v50
	v_mov_b32_e32 v69, v41
	v_mov_b32_e32 v41, v45
	v_mov_b32_e32 v68, v44
	v_mul_f32_e32 v54, s6, v54
	v_pk_mul_f32 v[40:41], v[40:41], v[132:133]
	v_pk_mul_f32 v[68:69], v[68:69], v[142:143]
	v_pk_mul_f32 v[40:41], v[40:41], v[54:55] op_sel_hi:[1,0]
	v_pk_mul_f32 v[44:45], v[68:69], v[54:55] op_sel_hi:[1,0]
	v_pk_mul_f32 v[68:69], v[64:65], v[40:41]
	v_mov_b32_e32 v70, v44
	v_pk_fma_f32 v[68:69], v[76:77], v[44:45], v[68:69]
	v_mov_b32_e32 v71, v41
	v_mov_b32_e32 v41, v45
	v_mov_b32_e32 v44, v46
	v_mov_b32_e32 v45, v43
	v_mov_b32_e32 v43, v47
	v_pk_mul_f32 v[44:45], v[44:45], v[124:125]
	v_pk_mul_f32 v[42:43], v[42:43], v[134:135]
	v_pk_mul_f32 v[40:41], v[60:61], v[40:41]
	v_pk_mul_f32 v[44:45], v[44:45], v[54:55] op_sel_hi:[1,0]
	v_pk_mul_f32 v[42:43], v[42:43], v[54:55] op_sel_hi:[1,0]
	v_add_u32_e32 v50, 0x90, v146
	v_pk_fma_f32 v[40:41], v[56:57], v[70:71], v[40:41] neg_lo:[0,0,1] neg_hi:[0,0,1]
	v_pk_mul_f32 v[46:47], v[80:81], v[42:43]
	v_mov_b32_e32 v71, v43
	v_mov_b32_e32 v43, v45
	v_ashrrev_i32_e32 v51, 31, v50
	v_mov_b32_e32 v70, v44
	v_pk_mul_f32 v[42:43], v[62:63], v[42:43]
	v_lshlrev_b64 v[50:51], 11, v[50:51]
	v_pk_fma_f32 v[46:47], v[90:91], v[44:45], v[46:47]
	v_pk_fma_f32 v[42:43], v[58:59], v[70:71], v[42:43] neg_lo:[0,0,1] neg_hi:[0,0,1]
	v_lshl_add_u64 v[50:51], v[138:139], 0, v[50:51]
	v_cvt_pk_bf16_f32 v40, v40, v41
	v_cvt_pk_bf16_f32 v41, v42, v43
	v_cvt_pk_bf16_f32 v42, v68, v69
	v_cvt_pk_bf16_f32 v43, v46, v47
	global_store_dwordx4 v[50:51], v[40:43], off
	v_mov_b32_e32 v45, v53
	v_mov_b32_e32 v44, v48
	v_mov_b32_e32 v41, v33
	v_mov_b32_e32 v33, v37
	v_mov_b32_e32 v40, v36
	v_pk_mul_f32 v[32:33], v[32:33], v[128:129]
	v_pk_mul_f32 v[40:41], v[40:41], v[122:123]
	v_pk_mul_f32 v[32:33], v[32:33], v[54:55] op_sel_hi:[1,0]
	v_pk_mul_f32 v[36:37], v[40:41], v[54:55] op_sel_hi:[1,0]
	v_pk_mul_f32 v[40:41], v[32:33], v[48:49]
	v_mov_b32_e32 v43, v33
	v_pk_fma_f32 v[40:41], v[36:37], v[52:53], v[40:41]
	v_mov_b32_e32 v33, v37
	v_mov_b32_e32 v37, v35
	v_mov_b32_e32 v35, v39
	v_mov_b32_e32 v42, v36
	v_mov_b32_e32 v53, v49
	v_mov_b32_e32 v36, v38
	v_pk_mul_f32 v[34:35], v[34:35], v[130:131]
	v_pk_mul_f32 v[32:33], v[32:33], v[52:53]
	v_pk_mul_f32 v[36:37], v[36:37], v[126:127]
	v_pk_mul_f32 v[34:35], v[34:35], v[54:55] op_sel_hi:[1,0]
	v_pk_fma_f32 v[32:33], v[42:43], v[44:45], v[32:33] neg_lo:[0,0,1] neg_hi:[0,0,1]
	v_pk_mul_f32 v[36:37], v[36:37], v[54:55] op_sel_hi:[1,0]
	v_pk_mul_f32 v[38:39], v[34:35], v[66:67]
	v_mov_b32_e32 v42, v36
	v_pk_fma_f32 v[38:39], v[36:37], v[78:79], v[38:39]
	v_cvt_pk_bf16_f32 v32, v32, v33
	v_mul_f32_e32 v33, v29, v29
	v_mul_f32_e32 v36, v31, v31
	v_fmac_f32_e32 v33, v28, v28
	v_fmac_f32_e32 v36, v30, v30
	v_mov_b32_e32 v43, v35
	v_mov_b32_e32 v35, v37
	v_add_f32_e32 v33, v33, v36
	v_mul_f32_e32 v36, v25, v25
	v_mul_f32_e32 v37, v27, v27
	v_fmac_f32_e32 v36, v24, v24
	v_fmac_f32_e32 v37, v26, v26
	v_add_f32_e32 v36, v36, v37
	v_add_f32_e32 v33, v33, v36
	v_mul_f32_e32 v36, v21, v21
	v_mul_f32_e32 v37, v23, v23
	v_fmac_f32_e32 v36, v20, v20
	v_fmac_f32_e32 v37, v22, v22
	v_add_f32_e32 v36, v36, v37
	v_add_f32_e32 v33, v33, v36
	v_mul_f32_e32 v36, v17, v17
	v_mul_f32_e32 v37, v19, v19
	v_fmac_f32_e32 v36, v16, v16
	v_fmac_f32_e32 v37, v18, v18
	v_add_f32_e32 v36, v36, v37
	v_add_f32_e32 v36, v33, v36
	ds_bpermute_b32 v37, v179, v36
	v_mov_b32_e32 v45, v79
	v_mov_b32_e32 v79, v67
	v_mov_b32_e32 v44, v66
	v_pk_mul_f32 v[34:35], v[34:35], v[78:79]
	s_and_b64 vcc, exec, s[4:5]
	v_pk_fma_f32 v[34:35], v[42:43], v[44:45], v[34:35] neg_lo:[0,0,1] neg_hi:[0,0,1]
	v_mov_b32_e32 v42, 0
	v_cvt_pk_bf16_f32 v33, v34, v35
	v_cvt_pk_bf16_f32 v34, v40, v41
	v_cvt_pk_bf16_f32 v35, v38, v39
	global_store_dwordx4 v[50:51], v[32:35], off offset:64
	v_mov_b32_e32 v44, 0
	v_mov_b32_e32 v45, 1.0
	s_waitcnt lgkmcnt(0)
	v_add_f32_e32 v33, v36, v37
	ds_bpermute_b32 v43, v204, v33
	v_mov_b32_e32 v32, 1.0
	v_mov_b32_e32 v34, 1.0
	v_mov_b32_e32 v35, 0
	v_mov_b32_e32 v38, 1.0
	v_mov_b32_e32 v36, 0
	v_mov_b32_e32 v37, 1.0
	v_mov_b32_e32 v39, 0
	s_cbranch_vccnz .LBB0_377
	s_waitcnt vmcnt(6)
	v_lshlrev_b32_e32 v168, 3, v172
	v_lshl_add_u64 v[38:39], v[180:181], 0, v[168:169]
	v_lshl_add_u64 v[34:35], v[38:39], 0, s[18:19]
	v_add_co_u32_e32 v38, vcc, 0x1000, v38
	v_mov_b32_e32 v34, v242
	v_mov_b32_e32 v35, v243
	v_mov_b32_e32 v36, v244
	v_mov_b32_e32 v37, v245
	s_nop 0
	v_addc_co_u32_e32 v39, vcc, 0, v39, vcc
	v_mov_b32_e32 v38, v248
	v_mov_b32_e32 v39, v249
	v_mov_b32_e32 v40, v250
	v_mov_b32_e32 v41, v251
	v_mov_b32_e32 v44, v35
	v_mov_b32_e32 v45, v36
	v_mov_b32_e32 v35, v37
	v_mov_b32_e32 v36, v39
	v_mov_b32_e32 v37, v40
	v_mov_b32_e32 v39, v41
; __device__ __forceinline__ unsigned cvtpk(float lo, float hi) { f32x2 v = {lo, hi}; bf16x2_t b = __builtin_convertvector(v, bf16x2_t); return __builtin_bit_cast(unsigned, b); }
;     __device__ __forceinline__ void operator()(const f32x4 (&acc)[2][2][4][2], const pg8::Unit& u, int wr, int wc, int fr, int fq) const {
;     ...
; #pragma unroll
;                 for (int m = 0; m < 4; ++m) {
;                     const int t = 256 * u.pm + 128 * ai + 64 * wr + 16 * m + fr;
;                     float ss = 0.f;
; #pragma unroll
;                     for (int bj = 0; bj < 2; ++bj)
; #pragma unroll
;                         for (int n = 0; n < 2; ++n) { const f32x4 v = acc[ai][bj][m][n]; ss += (v[0] * v[0] + v[1] * v[1]) + (v[2] * v[2] + v[3] * v[3]); }
;                     ss += __shfl_xor(ss, 16); ss += __shfl_xor(ss, 32);
;                     const float rstd = __builtin_amdgcn_rsqf(ss * (1.0f / 64.0f) + EPS) * osc;
;                     f32x4 cc0, cc1;
;                     if (kind == 0) { const f32x4* tp = (const f32x4*)(tab + (16 * m + fr) * 16 + 4 * fq); cc0 = tp[0]; cc1 = tp[1]; }
;                     else { cc0 = (f32x4){1.f, 0.f, 1.f, 0.f}; cc1 = cc0; }
;                     bf16_t* rowp = dst + (size_t)(rowoff + t) * 1024 + G * 64 + 8 * fq;
; #pragma unroll
;                     for (int bj = 0; bj < 2; ++bj) {
;                         const f32x4 x1 = acc[ai][bj][m][0] * g[bj][0] * rstd, x2 = acc[ai][bj][m][1] * g[bj][1] * rstd;
;                         const f32x4 ca = bj == 0 ? cr0 : cc0, cb = bj == 0 ? cr1 : cc1;
;                         const float co[4] = {ca[0], ca[2], cb[0], cb[2]}, si[4] = {ca[1], ca[3], cb[1], cb[3]};
;                         float o1[4], o2[4];
; #pragma unroll
;                         for (int e = 0; e < 4; ++e) { o1[e] = x1[e] * co[e] - x2[e] * si[e]; o2[e] = x2[e] * co[e] + x1[e] * si[e]; }
;                         u32x4 w; w.x = cvtpk(o1[0], o1[1]); w.y = cvtpk(o1[2], o1[3]); w.z = cvtpk(o2[0], o2[1]); w.w = cvtpk(o2[2], o2[3]);
;                         *(u32x4*)(rowp + 32 * bj) = w;
.LBB0_377:
	s_waitcnt lgkmcnt(0)
	v_add_f32_e32 v33, v33, v43
	v_fmamk_f32 v33, v33, 0x3c800000, v202
	v_rsq_f32_e32 v33, v33
	v_mov_b32_e32 v49, v25
	v_mov_b32_e32 v25, v29
	v_mov_b32_e32 v48, v28
	v_mul_f32_e32 v46, s6, v33
	v_pk_mul_f32 v[24:25], v[24:25], v[132:133]
	v_pk_mul_f32 v[48:49], v[48:49], v[142:143]
	v_pk_mul_f32 v[24:25], v[24:25], v[46:47] op_sel_hi:[1,0]
	v_pk_mul_f32 v[28:29], v[48:49], v[46:47] op_sel_hi:[1,0]
	v_pk_mul_f32 v[48:49], v[64:65], v[24:25]
	v_mov_b32_e32 v50, v28
	v_pk_fma_f32 v[48:49], v[76:77], v[28:29], v[48:49]
	v_mov_b32_e32 v51, v25
	v_mov_b32_e32 v25, v29
	v_mov_b32_e32 v28, v30
	v_mov_b32_e32 v29, v27
	v_mov_b32_e32 v27, v31
	v_pk_mul_f32 v[28:29], v[28:29], v[124:125]
	v_pk_mul_f32 v[26:27], v[26:27], v[134:135]
	v_pk_mul_f32 v[24:25], v[60:61], v[24:25]
	v_pk_mul_f32 v[28:29], v[28:29], v[46:47] op_sel_hi:[1,0]
	v_pk_mul_f32 v[26:27], v[26:27], v[46:47] op_sel_hi:[1,0]
	v_add_u32_e32 v40, 0xa0, v146
	v_pk_fma_f32 v[24:25], v[56:57], v[50:51], v[24:25] neg_lo:[0,0,1] neg_hi:[0,0,1]
	v_pk_mul_f32 v[30:31], v[80:81], v[26:27]
	v_mov_b32_e32 v51, v27
	v_mov_b32_e32 v27, v29
	v_ashrrev_i32_e32 v41, 31, v40
	v_mov_b32_e32 v50, v28
	v_pk_mul_f32 v[26:27], v[62:63], v[26:27]
	v_lshlrev_b64 v[40:41], 11, v[40:41]
	v_pk_fma_f32 v[30:31], v[90:91], v[28:29], v[30:31]
	v_pk_fma_f32 v[26:27], v[58:59], v[50:51], v[26:27] neg_lo:[0,0,1] neg_hi:[0,0,1]
	v_lshl_add_u64 v[40:41], v[138:139], 0, v[40:41]
	v_cvt_pk_bf16_f32 v24, v24, v25
	v_cvt_pk_bf16_f32 v25, v26, v27
	v_cvt_pk_bf16_f32 v26, v48, v49
	v_cvt_pk_bf16_f32 v27, v30, v31
	global_store_dwordx4 v[40:41], v[24:27], off
	v_mov_b32_e32 v29, v37
	v_mov_b32_e32 v28, v38
	v_mov_b32_e32 v25, v17
	v_mov_b32_e32 v17, v21
	v_mov_b32_e32 v24, v20
	v_pk_mul_f32 v[16:17], v[16:17], v[128:129]
	v_pk_mul_f32 v[24:25], v[24:25], v[122:123]
	v_pk_mul_f32 v[16:17], v[16:17], v[46:47] op_sel_hi:[1,0]
	v_pk_mul_f32 v[20:21], v[24:25], v[46:47] op_sel_hi:[1,0]
	v_pk_mul_f32 v[24:25], v[16:17], v[38:39]
	v_mov_b32_e32 v27, v17
	v_pk_fma_f32 v[24:25], v[20:21], v[36:37], v[24:25]
	v_mov_b32_e32 v17, v21
	v_mov_b32_e32 v21, v19
	v_mov_b32_e32 v19, v23
	v_mov_b32_e32 v26, v20
	v_mov_b32_e32 v37, v39
	v_mov_b32_e32 v20, v22
	v_pk_mul_f32 v[18:19], v[18:19], v[130:131]
	v_pk_mul_f32 v[16:17], v[16:17], v[36:37]
	v_pk_mul_f32 v[20:21], v[20:21], v[126:127]
	v_pk_mul_f32 v[18:19], v[18:19], v[46:47] op_sel_hi:[1,0]
	v_pk_fma_f32 v[16:17], v[26:27], v[28:29], v[16:17] neg_lo:[0,0,1] neg_hi:[0,0,1]
	v_pk_mul_f32 v[20:21], v[20:21], v[46:47] op_sel_hi:[1,0]
	v_pk_mul_f32 v[22:23], v[18:19], v[34:35]
	v_mov_b32_e32 v26, v20
	v_pk_fma_f32 v[22:23], v[20:21], v[44:45], v[22:23]
	v_cvt_pk_bf16_f32 v16, v16, v17
	v_mul_f32_e32 v17, v13, v13
	v_mul_f32_e32 v20, v15, v15
	v_fmac_f32_e32 v17, v12, v12
	v_fmac_f32_e32 v20, v14, v14
	v_mov_b32_e32 v27, v19
	v_mov_b32_e32 v19, v21
	v_add_f32_e32 v17, v17, v20
	v_mul_f32_e32 v20, v9, v9
	v_mul_f32_e32 v21, v11, v11
	v_fmac_f32_e32 v20, v8, v8
	v_fmac_f32_e32 v21, v10, v10
	v_add_f32_e32 v20, v20, v21
	v_add_f32_e32 v17, v17, v20
	v_mul_f32_e32 v20, v5, v5
	v_mul_f32_e32 v21, v7, v7
	v_fmac_f32_e32 v20, v4, v4
	v_fmac_f32_e32 v21, v6, v6
	v_add_f32_e32 v20, v20, v21
	v_add_f32_e32 v17, v17, v20
	v_mul_f32_e32 v20, v1, v1
	v_mul_f32_e32 v21, v3, v3
	v_fmac_f32_e32 v20, v0, v0
	v_fmac_f32_e32 v21, v2, v2
	v_add_f32_e32 v20, v20, v21
	v_add_f32_e32 v20, v17, v20
	ds_bpermute_b32 v21, v179, v20
	v_mov_b32_e32 v29, v45
	v_mov_b32_e32 v45, v35
	v_mov_b32_e32 v28, v34
	v_pk_mul_f32 v[18:19], v[18:19], v[44:45]
	s_and_b64 vcc, exec, s[4:5]
	v_pk_fma_f32 v[18:19], v[26:27], v[28:29], v[18:19] neg_lo:[0,0,1] neg_hi:[0,0,1]
	v_mov_b32_e32 v43, 1.0
	v_cvt_pk_bf16_f32 v17, v18, v19
	v_cvt_pk_bf16_f32 v19, v22, v23
	s_waitcnt lgkmcnt(0)
	v_add_f32_e32 v22, v20, v21
	ds_bpermute_b32 v23, v204, v22
	v_cvt_pk_bf16_f32 v18, v24, v25
	global_store_dwordx4 v[40:41], v[16:19], off offset:64
	v_mov_b32_e32 v33, 0
	v_mov_b32_e32 v20, 0
	v_mov_b32_e32 v16, 1.0
	v_mov_b32_e32 v21, 1.0
	v_mov_b32_e32 v17, 0
	s_cbranch_vccnz .LBB0_379
	s_waitcnt vmcnt(6)
	v_lshlrev_b32_e32 v168, 3, v172
	v_lshl_add_u64 v[16:17], v[180:181], 0, v[168:169]
	v_lshl_add_u64 v[18:19], v[16:17], 0, s[30:31]
	v_add_co_u32_e32 v16, vcc, 0x1000, v16
	v_mov_b32_e32 v32, v216
	v_mov_b32_e32 v33, v217
	v_mov_b32_e32 v34, v218
	v_mov_b32_e32 v35, v219
	s_nop 0
	v_addc_co_u32_e32 v17, vcc, 0, v17, vcc
	v_mov_b32_e32 v16, v230
	v_mov_b32_e32 v17, v231
	v_mov_b32_e32 v18, v232
	v_mov_b32_e32 v19, v233
	v_mov_b32_e32 v42, v33
	v_mov_b32_e32 v43, v34
	v_mov_b32_e32 v33, v35
	v_mov_b32_e32 v20, v17
	v_mov_b32_e32 v21, v18
	v_mov_b32_e32 v17, v19
